# v32 + stage C query-operand loads also as global loads (all VMEM ops ahead of the counted waits are global)
# speedup vs baseline: 1.0083x; 1.0014x over previous
; DI void nsa_phase(unsigned char* lds, KParamPtr P, int wv) {
;     ...
;           else if (cbm < 127) { u3 &= (2u << (cbm - 96)) - 1u; }
;         }
;         auto next_blk = [&]() -> int {
;           if (u0) { int bq = __builtin_ctz(u0); u0 &= u0 - 1u; return bq; }
;           if (u1) { int bq = __builtin_ctz(u1); u1 &= u1 - 1u; return 32 + bq; }
;           if (u2) { int bq = __builtin_ctz(u2); u2 &= u2 - 1u; return 64 + bq; }
;           if (u3) { int bq = __builtin_ctz(u3); u3 &= u3 - 1u; return 96 + bq; }
;           return -1;
;         };
;         bf16x8 qf[2];
; #pragma unroll
;         for (int st = 0; st < 2; ++st) qf[st] = ldg8(proj + tokq * EIN + C_NQ + hcol * 64 + st * 32 + q4 * 8);
.LBB0_1087:
	s_or_saveexec_b64 s[12:13], s[12:13]
	v_mov_b32_e32 v0, s28
	s_xor_b64 exec, exec, s[12:13]
	v_and_b32_e32 v0, s28, v128
	v_mov_b32_e32 v131, 0
	v_mov_b32_e32 v130, 0
	v_mov_b32_e32 v129, 0
	s_or_b64 exec, exec, s[12:13]
	v_or_b32_e32 v30, s2, v242
	v_or_b32_e32 v120, v30, v229
	v_ashrrev_i32_e32 v121, 31, v120
	v_lshl_add_u64 v[118:119], v[120:121], 0, v[182:183]
	v_mad_u64_u32 v[10:11], s[12:13], v118, s87, v[46:47]
	v_mad_i32_i24 v11, v119, s87, v11
	global_load_dwordx4 v[6:9], v[10:11], off
	s_nop 0
	global_load_dwordx4 v[10:13], v[10:11], off offset:64
	v_cmp_ne_u32_e32 vcc, 0, v0
	s_and_saveexec_b64 s[12:13], vcc
	s_xor_b64 s[12:13], exec, s[12:13]
	s_cbranch_execnz .LBB0_1148
	s_andn2_saveexec_b64 s[12:13], s[12:13]
	s_cbranch_execnz .LBB0_1149
